# HN: per-layer norm stores its bf16 h rows with the nt (streaming) policy (consumed next phase by other CUs), on top of C6+N3
# baseline (speedup 1.0000x reference)
.LBB0_391:
	v_mov_b32_e32 v0, s17
	v_mov_b32_e32 v1, s11
	v_cmp_gt_i32_e32 vcc, s85, v159
	v_mov_b32_e32 v2, s10
	v_mov_b32_e32 v145, v129
	v_cndmask_b32_e32 v1, v0, v1, vcc
	v_mov_b32_e32 v0, s16
	v_cndmask_b32_e32 v0, v0, v2, vcc
	v_add_u32_e32 v2, 0xfffff000, v159
	v_ashrrev_i32_e32 v2, 11, v2
	v_add_u32_e32 v2, 1, v2
	v_cndmask_b32_e64 v2, v2, 0, vcc
	v_mul_hi_i32_i24_e32 v3, 0x6000, v2
	v_mul_i32_i24_e32 v2, 0x6000, v2
	v_lshl_add_u64 v[2:3], s[26:27], 0, v[2:3]
	v_lshl_add_u64 v[4:5], v[2:3], 0, s[20:21]
	v_lshl_add_u64 v[6:7], v[4:5], 0, v[128:129]
	v_mov_b32_e32 v147, v129
	v_lshl_add_u64 v[0:1], v[0:1], 0, v[140:141]
	v_lshl_add_u64 v[8:9], v[2:3], 0, v[128:129]
	global_load_dwordx4 v[112:115], v[6:7], off
	global_load_dwordx4 v[116:119], v[8:9], off
	global_load_dwordx4 v[120:123], v[0:1], off offset:-4096
	global_load_dwordx4 v[100:103], v[0:1], off offset:-3072
	v_lshl_add_u64 v[6:7], v[4:5], 0, v[144:145]
	v_lshl_add_u64 v[10:11], v[4:5], 0, v[146:147]
	v_mov_b32_e32 v149, v129
	v_mov_b32_e32 v151, v129
	global_load_dwordx4 v[96:99], v[8:9], off offset:1024
	global_load_dwordx4 v[80:83], v[8:9], off offset:2048
	global_load_dwordx4 v[88:91], v[0:1], off offset:-2048
	global_load_dwordx4 v[72:75], v[0:1], off offset:-1024
	v_lshl_add_u64 v[12:13], v[4:5], 0, v[148:149]
	global_load_dwordx4 v[84:87], v[10:11], off
	global_load_dwordx4 v[64:67], v[12:13], off
	global_load_dwordx4 v[108:111], v[6:7], off
	global_load_dwordx4 v[68:71], v[8:9], off offset:3072
	v_lshl_add_u64 v[6:7], v[4:5], 0, v[150:151]
	v_lshl_add_u64 v[8:9], v[2:3], 0, v[150:151]
	v_mov_b32_e32 v153, v129
	global_load_dwordx4 v[48:51], v[6:7], off
	global_load_dwordx4 v[52:55], v[8:9], off
	global_load_dwordx4 v[56:59], v[0:1], off
	global_load_dwordx4 v[40:43], v[0:1], off offset:1024
	v_lshl_add_u64 v[6:7], v[4:5], 0, v[152:153]
	v_lshl_add_u64 v[8:9], v[2:3], 0, v[152:153]
	v_mov_b32_e32 v155, v129
	global_load_dwordx4 v[32:35], v[6:7], off
	global_load_dwordx4 v[36:39], v[8:9], off
	v_lshl_add_u64 v[6:7], v[4:5], 0, v[154:155]
	v_lshl_add_u64 v[8:9], v[2:3], 0, v[154:155]
	global_load_dwordx4 v[16:19], v[6:7], off
	global_load_dwordx4 v[20:23], v[8:9], off
	global_load_dwordx4 v[24:27], v[0:1], off offset:2048
	s_nop 0
	global_load_dwordx4 v[8:11], v[0:1], off offset:3072
	v_mov_b32_e32 v157, v129
	v_lshl_add_u64 v[0:1], v[4:5], 0, v[156:157]
	v_lshl_add_u64 v[4:5], v[2:3], 0, v[156:157]
	global_load_dwordx4 v[0:3], v[0:1], off
	s_nop 0
	global_load_dwordx4 v[4:7], v[4:5], off
	s_waitcnt vmcnt(0)
	v_mov_b64_e32 v[124:125], v[170:171]
	v_mov_b64_e32 v[126:127], v[172:173]
	v_mov_b64_e32 v[104:105], v[174:175]
	v_mov_b64_e32 v[106:107], v[176:177]
	v_mov_b64_e32 v[92:93], v[178:179]
	v_mov_b64_e32 v[94:95], v[180:181]
	v_mov_b64_e32 v[76:77], v[182:183]
	v_mov_b64_e32 v[78:79], v[184:185]
	v_mov_b64_e32 v[60:61], v[186:187]
	v_mov_b64_e32 v[62:63], v[188:189]
	v_mov_b64_e32 v[44:45], v[190:191]
	v_mov_b64_e32 v[46:47], v[192:193]
	v_mov_b64_e32 v[28:29], v[194:195]
	v_mov_b64_e32 v[30:31], v[196:197]
	v_mov_b64_e32 v[12:13], v[198:199]
	v_mov_b64_e32 v[14:15], v[200:201]
	v_mul_f32_e32 v145, v121, v121
	v_mul_f32_e32 v147, v101, v101
	v_fmac_f32_e32 v145, v120, v120
	v_fmac_f32_e32 v147, v100, v100
	v_fmac_f32_e32 v145, v122, v122
	v_fmac_f32_e32 v147, v102, v102
	v_fmac_f32_e32 v145, v123, v123
	v_fmac_f32_e32 v147, v103, v103
	v_add_f32_e32 v145, v145, v147
	v_mul_f32_e32 v147, v89, v89
	v_fmac_f32_e32 v147, v88, v88
	v_fmac_f32_e32 v147, v90, v90
	v_fmac_f32_e32 v147, v91, v91
	v_add_f32_e32 v145, v145, v147
	v_mul_f32_e32 v147, v73, v73
	v_mov_b32_e32 v168, v57
	v_mov_b32_e32 v169, v41
	v_fmac_f32_e32 v147, v72, v72
	v_mov_b32_e32 v166, v56
	v_mov_b32_e32 v167, v40
	v_pk_mul_f32 v[168:169], v[168:169], v[168:169]
	v_fmac_f32_e32 v147, v74, v74
	v_pk_fma_f32 v[166:167], v[166:167], v[166:167], v[168:169]
	v_mov_b32_e32 v168, v58
	v_mov_b32_e32 v169, v42
	v_fmac_f32_e32 v147, v75, v75
	v_pk_fma_f32 v[166:167], v[168:169], v[168:169], v[166:167]
	v_mov_b32_e32 v168, v59
	v_mov_b32_e32 v169, v43
	v_add_f32_e32 v145, v145, v147
	v_pk_fma_f32 v[166:167], v[168:169], v[168:169], v[166:167]
	v_mov_b32_e32 v168, v25
	v_add_f32_e32 v145, v145, v166
	v_mov_b32_e32 v169, v9
	v_add_f32_e32 v145, v145, v167
	v_mov_b32_e32 v166, v24
	v_mov_b32_e32 v167, v8
	v_pk_mul_f32 v[168:169], v[168:169], v[168:169]
	v_pk_add_f32 v[112:113], v[112:113], 1.0 op_sel_hi:[1,0]
	v_pk_fma_f32 v[166:167], v[166:167], v[166:167], v[168:169]
	v_mov_b32_e32 v168, v26
	v_mov_b32_e32 v169, v10
	v_pk_fma_f32 v[166:167], v[168:169], v[168:169], v[166:167]
	v_mov_b32_e32 v168, v27
	v_mov_b32_e32 v169, v11
	v_pk_fma_f32 v[166:167], v[168:169], v[168:169], v[166:167]
	v_pk_add_f32 v[84:85], v[84:85], 1.0 op_sel_hi:[1,0]
	v_add_f32_e32 v145, v145, v166
	v_add_f32_e32 v145, v145, v167
	ds_bpermute_b32 v147, v160, v145
	v_pk_add_f32 v[64:65], v[64:65], 1.0 op_sel_hi:[1,0]
	v_pk_add_f32 v[48:49], v[48:49], 1.0 op_sel_hi:[1,0]
	v_pk_add_f32 v[32:33], v[32:33], 1.0 op_sel_hi:[1,0]
	v_pk_add_f32 v[16:17], v[16:17], 1.0 op_sel_hi:[1,0]
	s_waitcnt lgkmcnt(0)
	v_add_f32_e32 v145, v145, v147
	ds_bpermute_b32 v147, v161, v145
	v_pk_add_f32 v[0:1], v[0:1], 1.0 op_sel_hi:[1,0]
	v_pk_add_f32 v[114:115], v[114:115], 1.0 op_sel_hi:[1,0]
	v_pk_add_f32 v[86:87], v[86:87], 1.0 op_sel_hi:[1,0]
	v_pk_add_f32 v[66:67], v[66:67], 1.0 op_sel_hi:[1,0]
	s_waitcnt lgkmcnt(0)
	v_add_f32_e32 v145, v145, v147
	ds_bpermute_b32 v147, v162, v145
	v_pk_add_f32 v[50:51], v[50:51], 1.0 op_sel_hi:[1,0]
	v_pk_add_f32 v[34:35], v[34:35], 1.0 op_sel_hi:[1,0]
	v_pk_add_f32 v[18:19], v[18:19], 1.0 op_sel_hi:[1,0]
	v_pk_add_f32 v[2:3], v[2:3], 1.0 op_sel_hi:[1,0]
	s_waitcnt lgkmcnt(0)
	v_add_f32_e32 v145, v145, v147
	ds_bpermute_b32 v147, v163, v145
	v_lshl_add_u64 v[140:141], v[140:141], 0, s[18:19]
	s_waitcnt lgkmcnt(0)
	v_add_f32_e32 v145, v145, v147
	ds_bpermute_b32 v147, v164, v145
	s_waitcnt lgkmcnt(0)
	v_add_f32_e32 v145, v145, v147
	ds_bpermute_b32 v147, v165, v145
	s_waitcnt lgkmcnt(0)
	v_add_f32_e32 v145, v145, v147
	v_fmamk_f32 v145, v145, 0x3a000000, v234
	v_cmp_gt_f32_e32 vcc, s25, v145
	v_mul_f32_e32 v147, 0x4b800000, v145
	s_nop 0
	v_cndmask_b32_e32 v145, v145, v147, vcc
	v_rsq_f32_e32 v145, v145
	s_nop 0
	v_mul_f32_e32 v147, 0x45800000, v145
	v_cndmask_b32_e32 v158, v145, v147, vcc
	v_pk_mul_f32 v[120:121], v[120:121], v[158:159] op_sel_hi:[1,0]
	v_pk_mul_f32 v[100:101], v[100:101], v[158:159] op_sel_hi:[1,0]
	v_pk_mul_f32 v[88:89], v[88:89], v[158:159] op_sel_hi:[1,0]
	v_pk_mul_f32 v[72:73], v[72:73], v[158:159] op_sel_hi:[1,0]
	v_pk_mul_f32 v[56:57], v[56:57], v[158:159] op_sel_hi:[1,0]
	v_pk_mul_f32 v[40:41], v[40:41], v[158:159] op_sel_hi:[1,0]
	v_pk_mul_f32 v[24:25], v[24:25], v[158:159] op_sel_hi:[1,0]
	v_pk_mul_f32 v[8:9], v[8:9], v[158:159] op_sel_hi:[1,0]
	v_pk_mul_f32 v[120:121], v[124:125], v[120:121]
	v_pk_mul_f32 v[100:101], v[104:105], v[100:101]
	v_pk_add_f32 v[104:105], v[108:109], 1.0 op_sel_hi:[1,0]
	v_pk_mul_f32 v[88:89], v[92:93], v[88:89]
	v_pk_mul_f32 v[72:73], v[76:77], v[72:73]
	v_pk_mul_f32 v[56:57], v[60:61], v[56:57]
	v_pk_mul_f32 v[40:41], v[44:45], v[40:41]
	v_pk_mul_f32 v[24:25], v[28:29], v[24:25]
	v_pk_mul_f32 v[8:9], v[12:13], v[8:9]
	v_pk_fma_f32 v[112:113], v[112:113], v[120:121], v[116:117]
	v_pk_mul_f32 v[116:117], v[122:123], v[158:159] op_sel_hi:[1,0]
	v_pk_fma_f32 v[96:97], v[104:105], v[100:101], v[96:97]
	v_pk_mul_f32 v[100:101], v[102:103], v[158:159] op_sel_hi:[1,0]
	v_pk_fma_f32 v[80:81], v[84:85], v[88:89], v[80:81]
	v_pk_mul_f32 v[84:85], v[90:91], v[158:159] op_sel_hi:[1,0]
	v_pk_fma_f32 v[64:65], v[64:65], v[72:73], v[68:69]
	v_pk_mul_f32 v[68:69], v[74:75], v[158:159] op_sel_hi:[1,0]
	v_pk_fma_f32 v[48:49], v[48:49], v[56:57], v[52:53]
	v_pk_mul_f32 v[52:53], v[58:59], v[158:159] op_sel_hi:[1,0]
	v_pk_fma_f32 v[32:33], v[32:33], v[40:41], v[36:37]
	v_pk_mul_f32 v[36:37], v[42:43], v[158:159] op_sel_hi:[1,0]
	v_pk_fma_f32 v[16:17], v[16:17], v[24:25], v[20:21]
	v_pk_mul_f32 v[20:21], v[26:27], v[158:159] op_sel_hi:[1,0]
	v_pk_fma_f32 v[0:1], v[0:1], v[8:9], v[4:5]
	v_pk_mul_f32 v[4:5], v[10:11], v[158:159] op_sel_hi:[1,0]
	v_pk_mul_f32 v[116:117], v[126:127], v[116:117]
	v_pk_mul_f32 v[100:101], v[106:107], v[100:101]
	v_pk_add_f32 v[102:103], v[110:111], 1.0 op_sel_hi:[1,0]
	v_pk_mul_f32 v[84:85], v[94:95], v[84:85]
	v_pk_mul_f32 v[68:69], v[78:79], v[68:69]
	v_pk_mul_f32 v[52:53], v[62:63], v[52:53]
	v_pk_mul_f32 v[36:37], v[46:47], v[36:37]
	v_pk_mul_f32 v[20:21], v[30:31], v[20:21]
	v_pk_mul_f32 v[4:5], v[14:15], v[4:5]
	v_pk_fma_f32 v[114:115], v[114:115], v[116:117], v[118:119]
	v_pk_fma_f32 v[98:99], v[102:103], v[100:101], v[98:99]
	v_pk_fma_f32 v[82:83], v[86:87], v[84:85], v[82:83]
	v_pk_fma_f32 v[66:67], v[66:67], v[68:69], v[70:71]
	v_pk_fma_f32 v[50:51], v[50:51], v[52:53], v[54:55]
	v_pk_fma_f32 v[34:35], v[34:35], v[36:37], v[38:39]
	v_pk_fma_f32 v[18:19], v[18:19], v[20:21], v[22:23]
	v_pk_fma_f32 v[2:3], v[2:3], v[4:5], v[6:7]
	v_add_u32_e32 v159, s6, v159
	v_cvt_pk_bf16_f32 v112, v112, v113
	v_cvt_pk_bf16_f32 v113, v114, v115
	v_cvt_pk_bf16_f32 v96, v96, v97
	v_cvt_pk_bf16_f32 v97, v98, v99
	v_cvt_pk_bf16_f32 v80, v80, v81
	v_cvt_pk_bf16_f32 v81, v82, v83
	v_cvt_pk_bf16_f32 v64, v64, v65
	v_cvt_pk_bf16_f32 v65, v66, v67
	v_cvt_pk_bf16_f32 v48, v48, v49
	v_cvt_pk_bf16_f32 v49, v50, v51
	v_cvt_pk_bf16_f32 v32, v32, v33
	v_cvt_pk_bf16_f32 v33, v34, v35
	v_cvt_pk_bf16_f32 v16, v16, v17
	v_cvt_pk_bf16_f32 v17, v18, v19
	v_cvt_pk_bf16_f32 v0, v0, v1
	v_cvt_pk_bf16_f32 v1, v2, v3
	v_cmp_lt_i32_e32 vcc, s7, v159
	global_store_dwordx2 v[142:143], v[112:113], off offset:-2048 nt
	global_store_dwordx2 v[142:143], v[96:97], off offset:-1536 nt
	global_store_dwordx2 v[142:143], v[80:81], off offset:-1024 nt
	global_store_dwordx2 v[142:143], v[64:65], off offset:-512 nt
	global_store_dwordx2 v[142:143], v[48:49], off nt
	global_store_dwordx2 v[142:143], v[32:33], off offset:512 nt
	global_store_dwordx2 v[142:143], v[16:17], off offset:1024 nt
	global_store_dwordx2 v[142:143], v[0:1], off offset:1536 nt
	v_lshl_add_u64 v[142:143], v[142:143], 0, s[8:9]
	s_or_b64 s[4:5], vcc, s[4:5]
	s_andn2_b64 exec, exec, s[4:5]
	s_cbranch_execnz .LBB0_391
